# MoBA items fill the LDS Q-row buffer from the already-loaded Q fragments instead of loading the 64 rows a second time
# speedup vs baseline: 1.0012x; 1.0012x over previous
; DI void attn_b_item(unsigned char* ws, LAS unsigned char* buf, LAS unsigned char* qbuf, LAS unsigned* tbl, LAS float* km  , int bh, int qblk, int w4, int lane) {
;     ...
;     QT a, b; qt_init(a, Q + (size_t)qpa * 64, h); qt_init(b, Q + (size_t)qpb * 64, h);
;     TileRegs tr;
;     tile_gload(tr, Q, Q + 32 * 64, qblk * 256 + w4 * 64, 1, lane); tile_lds_write(qbuf, tr, lane);
.LBB0_537:
	s_bfe_u32 s18, s2, 0x30003
	s_and_b32 s19, s1, 1
	s_bitcmp1_b32 s1, 0
	s_cselect_b64 s[16:17], -1, 0
	s_xor_b64 s[16:17], s[72:73], s[16:17]
	s_xor_b32 s20, s18, 15
	s_and_b64 s[16:17], s[16:17], exec
	s_cselect_b32 s57, s20, s18
	s_cmp_eq_u32 s19, 0
	s_cselect_b32 s82, s23, s97
	s_lshl_b32 s16, s56, 19
	s_add_u32 s16, s66, s16
	s_addc_u32 s17, s67, 0
	s_lshl_b32 s80, s57, 8
	s_lshl_b32 s18, s82, 6
	s_or_b32 s20, s18, s80
	v_or_b32_e32 v246, s20, v214
	v_lshlrev_b32_e32 v114, 7, v246
	v_lshl_add_u64 v[0:1], s[16:17], 0, v[114:115]
	v_lshlrev_b32_e32 v182, 4, v180
	v_mov_b32_e32 v183, v115
	v_or_b32_e32 v188, 32, v246
	v_lshl_add_u64 v[0:1], v[0:1], 0, v[182:183]
	v_mov_b32_e32 v189, v115
	global_load_dword v247, v115, s[74:75]
	global_load_dwordx4 v[116:119], v[0:1], off
	global_load_dwordx4 v[120:123], v[0:1], off offset:32
	global_load_dwordx4 v[124:127], v[0:1], off offset:64
	global_load_dwordx4 v[128:131], v[0:1], off offset:96
	v_lshlrev_b64 v[0:1], 7, v[188:189]
	v_lshl_add_u64 v[0:1], s[16:17], 0, v[0:1]
	v_lshl_add_u64 v[32:33], v[0:1], 0, v[182:183]
	v_or_b32_e32 v0, s20, v215
	v_or_b32_e32 v8, s20, v217
	v_or_b32_e32 v16, s20, v218
	s_add_u32 s18, s16, 0x1000
	v_lshl_or_b32 v4, v0, 7, v216
	v_lshl_or_b32 v12, v8, 7, v216
	v_lshl_or_b32 v20, v16, 7, v216
	s_addc_u32 s19, s17, 0
	v_or_b32_e32 v24, s20, v219
	v_lshl_or_b32 v28, v24, 7, v216
	global_load_dwordx4 v[132:135], v[32:33], off
	global_load_dwordx4 v[136:139], v[32:33], off offset:32
	global_load_dwordx4 v[140:143], v[32:33], off offset:64
	global_load_dwordx4 v[144:147], v[32:33], off offset:96
	v_cndmask_b32_e64 v32, 0, 1, s[76:77]
	s_cmp_lg_u32 s57, 0
	v_and_b32_e32 v0, 31, v234
	v_mul_u32_u24_e32 v0, 0x90, v0
	v_bfe_u32 v1, v234, 5, 1
	v_lshl_add_u32 v0, v1, 4, v0
	v_add_u32_e32 v33, s95, v0
	v_lshl_add_u32 v32, v32, 12, v238
	s_cselect_b64 s[18:19], -1, 0
	s_cmp_eq_u32 s57, 0
	s_waitcnt vmcnt(4)
	ds_write_b128 v33, v[116:119]
	ds_write_b128 v33, v[120:123] offset:32
	ds_write_b128 v33, v[124:127] offset:64
	ds_write_b128 v33, v[128:131] offset:96
	s_waitcnt vmcnt(0)
	ds_write_b128 v33, v[132:135] offset:4608
	ds_write_b128 v33, v[136:139] offset:4640
	ds_write_b128 v33, v[140:143] offset:4672
	ds_write_b128 v33, v[144:147] offset:4704
	s_cbranch_scc1 .LBB0_547
	v_and_b32_e32 v1, 64, v244
	v_xor_b32_e32 v0, 32, v244
	v_add_u32_e32 v1, 64, v1
	v_cmp_lt_i32_e32 vcc, v0, v1
	s_mov_b32 s81, 0
	v_lshlrev_b32_e32 v1, 16, v120
	v_cndmask_b32_e32 v0, v244, v0, vcc
	v_lshlrev_b32_e32 v36, 2, v0
	v_lshlrev_b32_e32 v0, 16, v116
	v_and_b32_e32 v3, 0xffff0000, v120
	v_and_b32_e32 v2, 0xffff0000, v116
	v_lshlrev_b32_e32 v5, 16, v121
	v_lshlrev_b32_e32 v4, 16, v117
	v_and_b32_e32 v7, 0xffff0000, v121
	v_and_b32_e32 v6, 0xffff0000, v117
	v_lshlrev_b32_e32 v9, 16, v122
	v_lshlrev_b32_e32 v8, 16, v118
	v_and_b32_e32 v11, 0xffff0000, v122
	v_and_b32_e32 v10, 0xffff0000, v118
	v_lshlrev_b32_e32 v13, 16, v123
	v_lshlrev_b32_e32 v12, 16, v119
	v_and_b32_e32 v15, 0xffff0000, v123
	v_and_b32_e32 v14, 0xffff0000, v119
	v_lshlrev_b32_e32 v17, 16, v128
	v_lshlrev_b32_e32 v16, 16, v124
	v_and_b32_e32 v19, 0xffff0000, v128
	v_and_b32_e32 v18, 0xffff0000, v124
	v_lshlrev_b32_e32 v21, 16, v129
	v_lshlrev_b32_e32 v20, 16, v125
	v_and_b32_e32 v23, 0xffff0000, v129
	v_and_b32_e32 v22, 0xffff0000, v125
	v_lshlrev_b32_e32 v25, 16, v130
	v_lshlrev_b32_e32 v24, 16, v126
	v_and_b32_e32 v27, 0xffff0000, v130
	v_and_b32_e32 v26, 0xffff0000, v126
	v_lshlrev_b32_e32 v29, 16, v131
	v_lshlrev_b32_e32 v28, 16, v127
	v_and_b32_e32 v31, 0xffff0000, v131
	v_and_b32_e32 v30, 0xffff0000, v127
	v_mov_b32_e32 v39, 31
	v_mov_b32_e32 v38, 0xff61b1e6
	v_mov_b32_e32 v37, 0xff61b1e6
	v_mov_b32_e32 v40, 0xff61b1e6
	s_mov_b32 s83, 0
	v_mov_b32_e32 v41, 31
	v_mov_b32_e32 v33, 31
